# attention loop: cross-half max exchange only in the rescale path; row-sum kept per half-wave and combined once at item exit (8 fewer VALU/iteration)
# speedup vs baseline: 1.0075x; 1.0075x over previous
.LBB0_1480:
	v_readfirstlane_b32 s44, v203
	v_readfirstlane_b32 s45, v205
	s_mov_b64 s[40:41], s[94:95]
	s_mov_b64 s[42:43], s[94:95]
	s_movk_i32 s46, 0x41
	s_add_u32 s45, s45, 0x2000
	v_mul_f32_e32 v189, 0.5, v189
.Latt_loop:
	s_waitcnt vmcnt(0)
	s_barrier
	ds_read_b128 v[64:67], v173 offset:24576
	ds_read_b128 v[68:71], v173 offset:28672
	s_mov_b32 m0, s44
	ds_read_b128 v[72:75], v171 offset:24576
	global_load_lds_dwordx4 v200, s[40:41]
	s_add_u32 m0, s44, 0x400
	ds_read_b128 v[76:79], v171 offset:28672
	global_load_lds_dwordx4 v190, s[40:41]
	s_mov_b32 m0, s45
	ds_read_b128 v[216:219], v169 offset:24576
	global_load_lds_dwordx4 v192, s[42:43]
	s_add_u32 m0, s45, 0x400
	ds_read_b128 v[220:223], v169 offset:28672
	global_load_lds_dwordx4 v194, s[42:43]
	s_add_u32 m0, s45, 0x800
	ds_read_b128 v[224:227], v167 offset:24576
	global_load_lds_dwordx4 v196, s[42:43]
	s_add_u32 m0, s45, 0xc00
	ds_read_b128 v[228:231], v167 offset:28672
	global_load_lds_dwordx4 v198, s[42:43]
	ds_read_b128 v[232:235], v173 offset:32768
	ds_read_b128 v[236:239], v173 offset:36864
	ds_read_b128 v[240:243], v173 offset:40960
	ds_read_b128 v[244:247], v173 offset:45056
	s_add_u32 s40, s40, 0x18000
	s_addc_u32 s41, s41, 0
	s_add_u32 s42, s42, 0x80
	s_addc_u32 s43, s43, 0
	s_waitcnt lgkmcnt(11)
	v_mfma_f32_32x32x16_bf16 v[112:127], v[64:67], v[140:143], v[96:111]
	ds_read_b128 v[64:67], v171 offset:32768
	s_waitcnt lgkmcnt(11)
	v_mfma_f32_32x32x16_bf16 v[80:95], v[68:71], v[140:143], v[96:111]
	ds_read_b128 v[68:71], v171 offset:36864
	s_waitcnt lgkmcnt(11)
	v_mfma_f32_32x32x16_bf16 v[112:127], v[72:75], v[136:139], v[112:127]
	ds_read_b128 v[72:75], v171 offset:40960
	s_waitcnt lgkmcnt(11)
	v_mfma_f32_32x32x16_bf16 v[80:95], v[76:79], v[136:139], v[80:95]
	ds_read_b128 v[76:79], v171 offset:45056
	s_waitcnt lgkmcnt(11)
	v_mfma_f32_32x32x16_bf16 v[112:127], v[216:219], v[132:135], v[112:127]
	ds_read_b128 v[216:219], v169 offset:32768
	s_waitcnt lgkmcnt(11)
	v_mfma_f32_32x32x16_bf16 v[80:95], v[220:223], v[132:135], v[80:95]
	ds_read_b128 v[220:223], v169 offset:36864
	s_waitcnt lgkmcnt(11)
	v_mfma_f32_32x32x16_bf16 v[112:127], v[224:227], v[128:131], v[112:127]
	ds_read_b128 v[224:227], v169 offset:40960
	s_waitcnt lgkmcnt(11)
	v_mfma_f32_32x32x16_bf16 v[80:95], v[228:231], v[128:131], v[80:95]
	ds_read_b128 v[228:231], v169 offset:45056
	s_nop 7
	s_nop 3
	v_max3_f32 v175, v112, v113, v114
	v_max3_f32 v177, v115, v116, v117
	v_max3_f32 v179, v118, v119, v120
	v_max3_f32 v181, v121, v122, v123
	v_max3_f32 v248, v124, v125, v126
	v_max3_f32 v249, v127, v80, v81
	v_max3_f32 v250, v82, v83, v84
	v_max3_f32 v251, v85, v86, v87
	v_max3_f32 v253, v88, v89, v90
	v_max3_f32 v254, v91, v92, v93
	v_max_f32_e32 v255, v94, v95
	v_max3_f32 v175, v175, v177, v179
	v_max3_f32 v181, v181, v248, v249
	v_max3_f32 v250, v250, v251, v253
	v_max_f32_e32 v254, v254, v255
	v_max3_f32 v175, v175, v181, v250
	v_max_f32_e32 v175, v175, v254
	v_cmp_lt_f32_e32 vcc, 0, v175
	s_cbranch_vccnz .Latt_resc_a
.Latt_cont_a:
	v_exp_f32_e32 v112, v112
	v_exp_f32_e32 v113, v113
	v_exp_f32_e32 v114, v114
	v_exp_f32_e32 v115, v115
	v_exp_f32_e32 v116, v116
	v_exp_f32_e32 v117, v117
	v_exp_f32_e32 v118, v118
	v_exp_f32_e32 v119, v119
	v_add_f32_e32 v183, v112, v113
	v_add_f32_e32 v183, v183, v114
	v_add_f32_e32 v183, v183, v115
	v_add_f32_e32 v183, v183, v116
	v_add_f32_e32 v183, v183, v117
	v_add_f32_e32 v183, v183, v118
	v_add_f32_e32 v183, v183, v119
	v_cvt_pk_bf16_f32 v112, v112, v113
	v_cvt_pk_bf16_f32 v113, v114, v115
	v_cvt_pk_bf16_f32 v114, v116, v117
	v_cvt_pk_bf16_f32 v115, v118, v119
	v_exp_f32_e32 v120, v120
	v_exp_f32_e32 v121, v121
	s_waitcnt lgkmcnt(8)
	v_mfma_f32_32x32x16_bf16 v[48:63], v[232:235], v[112:115], v[48:63]
	v_exp_f32_e32 v122, v122
	v_exp_f32_e32 v123, v123
	v_exp_f32_e32 v124, v124
	v_mfma_f32_32x32x16_bf16 v[32:47], v[236:239], v[112:115], v[32:47]
	v_exp_f32_e32 v125, v125
	v_exp_f32_e32 v126, v126
	v_exp_f32_e32 v127, v127
	v_mfma_f32_32x32x16_bf16 v[16:31], v[240:243], v[112:115], v[16:31]
	v_add_f32_e32 v185, v120, v121
	v_add_f32_e32 v185, v185, v122
	v_add_f32_e32 v185, v185, v123
	v_add_f32_e32 v185, v185, v124
	v_add_f32_e32 v185, v185, v125
	v_add_f32_e32 v185, v185, v126
	v_mfma_f32_32x32x16_bf16 v[0:15], v[244:247], v[112:115], v[0:15]
	ds_read_b128 v[232:235], v167 offset:32768
	ds_read_b128 v[236:239], v167 offset:36864
	ds_read_b128 v[240:243], v167 offset:40960
	ds_read_b128 v[244:247], v167 offset:45056
	v_add_f32_e32 v185, v185, v127
	v_cvt_pk_bf16_f32 v116, v120, v121
	v_cvt_pk_bf16_f32 v117, v122, v123
	v_cvt_pk_bf16_f32 v118, v124, v125
	v_cvt_pk_bf16_f32 v119, v126, v127
	s_nop 0
	s_waitcnt lgkmcnt(8)
	v_mfma_f32_32x32x16_bf16 v[48:63], v[64:67], v[116:119], v[48:63]
	v_exp_f32_e32 v80, v80
	v_exp_f32_e32 v81, v81
	v_exp_f32_e32 v82, v82
	v_mfma_f32_32x32x16_bf16 v[32:47], v[68:71], v[116:119], v[32:47]
	v_exp_f32_e32 v83, v83
	v_exp_f32_e32 v84, v84
	v_exp_f32_e32 v85, v85
	v_mfma_f32_32x32x16_bf16 v[16:31], v[72:75], v[116:119], v[16:31]
	v_exp_f32_e32 v86, v86
	v_exp_f32_e32 v87, v87
	v_add_f32_e32 v187, v80, v81
	v_add_f32_e32 v187, v187, v82
	v_mfma_f32_32x32x16_bf16 v[0:15], v[76:79], v[116:119], v[0:15]
	v_add_f32_e32 v187, v187, v83
	v_add_f32_e32 v187, v187, v84
	v_add_f32_e32 v187, v187, v85
	v_add_f32_e32 v187, v187, v86
	v_add_f32_e32 v187, v187, v87
	v_cvt_pk_bf16_f32 v80, v80, v81
	v_cvt_pk_bf16_f32 v81, v82, v83
	v_cvt_pk_bf16_f32 v82, v84, v85
	v_cvt_pk_bf16_f32 v83, v86, v87
	s_nop 0
	s_waitcnt lgkmcnt(4)
	v_mfma_f32_32x32x16_bf16 v[48:63], v[216:219], v[80:83], v[48:63]
	v_exp_f32_e32 v88, v88
	v_exp_f32_e32 v89, v89
	v_exp_f32_e32 v90, v90
	v_mfma_f32_32x32x16_bf16 v[32:47], v[220:223], v[80:83], v[32:47]
	v_exp_f32_e32 v91, v91
	v_exp_f32_e32 v92, v92
	v_exp_f32_e32 v93, v93
	v_mfma_f32_32x32x16_bf16 v[16:31], v[224:227], v[80:83], v[16:31]
	v_exp_f32_e32 v94, v94
	v_exp_f32_e32 v95, v95
	v_add_f32_e32 v215, v88, v89
	v_add_f32_e32 v215, v215, v90
	v_mfma_f32_32x32x16_bf16 v[0:15], v[228:231], v[80:83], v[0:15]
	v_add_f32_e32 v215, v215, v91
	v_add_f32_e32 v215, v215, v92
	v_add_f32_e32 v215, v215, v93
	v_add_f32_e32 v215, v215, v94
	v_add_f32_e32 v215, v215, v95
	v_cvt_pk_bf16_f32 v84, v88, v89
	v_cvt_pk_bf16_f32 v85, v90, v91
	v_cvt_pk_bf16_f32 v86, v92, v93
	v_cvt_pk_bf16_f32 v87, v94, v95
	s_nop 0
	s_waitcnt lgkmcnt(0)
	v_mfma_f32_32x32x16_bf16 v[48:63], v[232:235], v[84:87], v[48:63]
	v_add_f32_e32 v183, v183, v185
	v_add_f32_e32 v187, v187, v215
	v_add_f32_e32 v183, v183, v187
	v_mfma_f32_32x32x16_bf16 v[32:47], v[236:239], v[84:87], v[32:47]
	v_mfma_f32_32x32x16_bf16 v[16:31], v[240:243], v[84:87], v[16:31]
	v_mfma_f32_32x32x16_bf16 v[0:15], v[244:247], v[84:87], v[0:15]
	v_add_f32_e32 v189, v189, v183
	s_waitcnt vmcnt(0)
	s_barrier
	ds_read_b128 v[64:67], v173 offset:0
	ds_read_b128 v[68:71], v173 offset:4096
	s_add_u32 m0, s44, 0x6000
	ds_read_b128 v[72:75], v171 offset:0
	global_load_lds_dwordx4 v200, s[40:41]
	s_add_u32 m0, s44, 0x6400
	ds_read_b128 v[76:79], v171 offset:4096
	global_load_lds_dwordx4 v190, s[40:41]
	s_add_u32 m0, s45, 0x6000
	ds_read_b128 v[216:219], v169 offset:0
	global_load_lds_dwordx4 v192, s[42:43]
	s_add_u32 m0, s45, 0x6400
	ds_read_b128 v[220:223], v169 offset:4096
	global_load_lds_dwordx4 v194, s[42:43]
	s_add_u32 m0, s45, 0x6800
	ds_read_b128 v[224:227], v167 offset:0
	global_load_lds_dwordx4 v196, s[42:43]
	s_add_u32 m0, s45, 0x6c00
	ds_read_b128 v[228:231], v167 offset:4096
	global_load_lds_dwordx4 v198, s[42:43]
	ds_read_b128 v[232:235], v173 offset:8192
	ds_read_b128 v[236:239], v173 offset:12288
	ds_read_b128 v[240:243], v173 offset:16384
	ds_read_b128 v[244:247], v173 offset:20480
	s_add_u32 s40, s40, 0x18000
	s_addc_u32 s41, s41, 0
	s_add_u32 s42, s42, 0x80
	s_addc_u32 s43, s43, 0
	s_waitcnt lgkmcnt(11)
	v_mfma_f32_32x32x16_bf16 v[112:127], v[64:67], v[140:143], v[96:111]
	ds_read_b128 v[64:67], v171 offset:8192
	s_waitcnt lgkmcnt(11)
	v_mfma_f32_32x32x16_bf16 v[80:95], v[68:71], v[140:143], v[96:111]
	ds_read_b128 v[68:71], v171 offset:12288
	s_waitcnt lgkmcnt(11)
	v_mfma_f32_32x32x16_bf16 v[112:127], v[72:75], v[136:139], v[112:127]
	ds_read_b128 v[72:75], v171 offset:16384
	s_waitcnt lgkmcnt(11)
	v_mfma_f32_32x32x16_bf16 v[80:95], v[76:79], v[136:139], v[80:95]
	ds_read_b128 v[76:79], v171 offset:20480
	s_waitcnt lgkmcnt(11)
	v_mfma_f32_32x32x16_bf16 v[112:127], v[216:219], v[132:135], v[112:127]
	ds_read_b128 v[216:219], v169 offset:8192
	s_waitcnt lgkmcnt(11)
	v_mfma_f32_32x32x16_bf16 v[80:95], v[220:223], v[132:135], v[80:95]
	ds_read_b128 v[220:223], v169 offset:12288
	s_waitcnt lgkmcnt(11)
	v_mfma_f32_32x32x16_bf16 v[112:127], v[224:227], v[128:131], v[112:127]
	ds_read_b128 v[224:227], v169 offset:16384
	s_waitcnt lgkmcnt(11)
	v_mfma_f32_32x32x16_bf16 v[80:95], v[228:231], v[128:131], v[80:95]
	ds_read_b128 v[228:231], v169 offset:20480
	s_nop 7
	s_nop 3
	v_max3_f32 v175, v112, v113, v114
	v_max3_f32 v177, v115, v116, v117
	v_max3_f32 v179, v118, v119, v120
	v_max3_f32 v181, v121, v122, v123
	v_max3_f32 v248, v124, v125, v126
	v_max3_f32 v249, v127, v80, v81
	v_max3_f32 v250, v82, v83, v84
	v_max3_f32 v251, v85, v86, v87
	v_max3_f32 v253, v88, v89, v90
	v_max3_f32 v254, v91, v92, v93
	v_max_f32_e32 v255, v94, v95
	v_max3_f32 v175, v175, v177, v179
	v_max3_f32 v181, v181, v248, v249
	v_max3_f32 v250, v250, v251, v253
	v_max_f32_e32 v254, v254, v255
	v_max3_f32 v175, v175, v181, v250
	v_max_f32_e32 v175, v175, v254
	v_cmp_lt_f32_e32 vcc, 0, v175
	s_cbranch_vccnz .Latt_resc_b
.Latt_cont_b:
	v_exp_f32_e32 v112, v112
	v_exp_f32_e32 v113, v113
	v_exp_f32_e32 v114, v114
	v_exp_f32_e32 v115, v115
	v_exp_f32_e32 v116, v116
	v_exp_f32_e32 v117, v117
	v_exp_f32_e32 v118, v118
	v_exp_f32_e32 v119, v119
	v_add_f32_e32 v183, v112, v113
	v_add_f32_e32 v183, v183, v114
	v_add_f32_e32 v183, v183, v115
	v_add_f32_e32 v183, v183, v116
	v_add_f32_e32 v183, v183, v117
	v_add_f32_e32 v183, v183, v118
	v_add_f32_e32 v183, v183, v119
	v_cvt_pk_bf16_f32 v112, v112, v113
	v_cvt_pk_bf16_f32 v113, v114, v115
	v_cvt_pk_bf16_f32 v114, v116, v117
	v_cvt_pk_bf16_f32 v115, v118, v119
	v_exp_f32_e32 v120, v120
	v_exp_f32_e32 v121, v121
	s_waitcnt lgkmcnt(8)
	v_mfma_f32_32x32x16_bf16 v[48:63], v[232:235], v[112:115], v[48:63]
	v_exp_f32_e32 v122, v122
	v_exp_f32_e32 v123, v123
	v_exp_f32_e32 v124, v124
	v_mfma_f32_32x32x16_bf16 v[32:47], v[236:239], v[112:115], v[32:47]
	v_exp_f32_e32 v125, v125
	v_exp_f32_e32 v126, v126
	v_exp_f32_e32 v127, v127
	v_mfma_f32_32x32x16_bf16 v[16:31], v[240:243], v[112:115], v[16:31]
	v_add_f32_e32 v185, v120, v121
	v_add_f32_e32 v185, v185, v122
	v_add_f32_e32 v185, v185, v123
	v_add_f32_e32 v185, v185, v124
	v_add_f32_e32 v185, v185, v125
	v_add_f32_e32 v185, v185, v126
	v_mfma_f32_32x32x16_bf16 v[0:15], v[244:247], v[112:115], v[0:15]
	ds_read_b128 v[232:235], v167 offset:8192
	ds_read_b128 v[236:239], v167 offset:12288
	ds_read_b128 v[240:243], v167 offset:16384
	ds_read_b128 v[244:247], v167 offset:20480
	v_add_f32_e32 v185, v185, v127
	v_cvt_pk_bf16_f32 v116, v120, v121
	v_cvt_pk_bf16_f32 v117, v122, v123
	v_cvt_pk_bf16_f32 v118, v124, v125
	v_cvt_pk_bf16_f32 v119, v126, v127
	s_nop 0
	s_waitcnt lgkmcnt(8)
	v_mfma_f32_32x32x16_bf16 v[48:63], v[64:67], v[116:119], v[48:63]
	v_exp_f32_e32 v80, v80
	v_exp_f32_e32 v81, v81
	v_exp_f32_e32 v82, v82
	v_mfma_f32_32x32x16_bf16 v[32:47], v[68:71], v[116:119], v[32:47]
	v_exp_f32_e32 v83, v83
	v_exp_f32_e32 v84, v84
	v_exp_f32_e32 v85, v85
	v_mfma_f32_32x32x16_bf16 v[16:31], v[72:75], v[116:119], v[16:31]
	v_exp_f32_e32 v86, v86
	v_exp_f32_e32 v87, v87
	v_add_f32_e32 v187, v80, v81
	v_add_f32_e32 v187, v187, v82
	v_mfma_f32_32x32x16_bf16 v[0:15], v[76:79], v[116:119], v[0:15]
	v_add_f32_e32 v187, v187, v83
	v_add_f32_e32 v187, v187, v84
	v_add_f32_e32 v187, v187, v85
	v_add_f32_e32 v187, v187, v86
	v_add_f32_e32 v187, v187, v87
	v_cvt_pk_bf16_f32 v80, v80, v81
	v_cvt_pk_bf16_f32 v81, v82, v83
	v_cvt_pk_bf16_f32 v82, v84, v85
	v_cvt_pk_bf16_f32 v83, v86, v87
	s_nop 0
	s_waitcnt lgkmcnt(4)
	v_mfma_f32_32x32x16_bf16 v[48:63], v[216:219], v[80:83], v[48:63]
	v_exp_f32_e32 v88, v88
	v_exp_f32_e32 v89, v89
	v_exp_f32_e32 v90, v90
	v_mfma_f32_32x32x16_bf16 v[32:47], v[220:223], v[80:83], v[32:47]
	v_exp_f32_e32 v91, v91
	v_exp_f32_e32 v92, v92
	v_exp_f32_e32 v93, v93
	v_mfma_f32_32x32x16_bf16 v[16:31], v[224:227], v[80:83], v[16:31]
	v_exp_f32_e32 v94, v94
	v_exp_f32_e32 v95, v95
	v_add_f32_e32 v215, v88, v89
	v_add_f32_e32 v215, v215, v90
	v_mfma_f32_32x32x16_bf16 v[0:15], v[228:231], v[80:83], v[0:15]
	v_add_f32_e32 v215, v215, v91
	v_add_f32_e32 v215, v215, v92
	v_add_f32_e32 v215, v215, v93
	v_add_f32_e32 v215, v215, v94
	v_add_f32_e32 v215, v215, v95
	v_cvt_pk_bf16_f32 v84, v88, v89
	v_cvt_pk_bf16_f32 v85, v90, v91
	v_cvt_pk_bf16_f32 v86, v92, v93
	v_cvt_pk_bf16_f32 v87, v94, v95
	s_nop 0
	s_waitcnt lgkmcnt(0)
	v_mfma_f32_32x32x16_bf16 v[48:63], v[232:235], v[84:87], v[48:63]
	v_add_f32_e32 v183, v183, v185
	v_add_f32_e32 v187, v187, v215
	v_add_f32_e32 v183, v183, v187
	v_mfma_f32_32x32x16_bf16 v[32:47], v[236:239], v[84:87], v[32:47]
	v_mfma_f32_32x32x16_bf16 v[16:31], v[240:243], v[84:87], v[16:31]
	v_mfma_f32_32x32x16_bf16 v[0:15], v[244:247], v[84:87], v[0:15]
	v_add_f32_e32 v189, v189, v183
	s_sub_u32 s46, s46, 1
	s_cmp_lg_u32 s46, 0
	s_cbranch_scc1 .Latt_loop
	v_mov_b64_e32 v[64:65], v[96:97]
	v_mov_b64_e32 v[66:67], v[98:99]
	v_mov_b64_e32 v[68:69], v[100:101]
	v_mov_b64_e32 v[70:71], v[102:103]
	v_mov_b64_e32 v[72:73], v[104:105]
	v_mov_b64_e32 v[74:75], v[106:107]
	v_mov_b64_e32 v[76:77], v[108:109]
	v_mov_b64_e32 v[78:79], v[110:111]
	v_mov_b32_e32 v248, v189
	s_nop 1
	v_permlane32_swap_b32_e32 v189, v248
	v_add_f32_e32 v189, v189, v248
	s_branch .LBB0_1482
.Latt_resc_a:
	v_mov_b32_e32 v177, v175
	s_nop 1
	v_permlane32_swap_b32_e32 v175, v177
	v_max_f32_e32 v175, v175, v177
	v_max_f32_e32 v248, 0, v175
	v_exp_f32_e64 v250, -v248
	v_sub_f32_e32 v112, v112, v248
	v_sub_f32_e32 v113, v113, v248
	v_sub_f32_e32 v114, v114, v248
	v_sub_f32_e32 v115, v115, v248
	v_sub_f32_e32 v116, v116, v248
	v_sub_f32_e32 v117, v117, v248
	v_sub_f32_e32 v118, v118, v248
	v_sub_f32_e32 v119, v119, v248
	v_sub_f32_e32 v120, v120, v248
	v_sub_f32_e32 v121, v121, v248
	v_sub_f32_e32 v122, v122, v248
	v_sub_f32_e32 v123, v123, v248
	v_sub_f32_e32 v124, v124, v248
	v_sub_f32_e32 v125, v125, v248
	v_sub_f32_e32 v126, v126, v248
	v_sub_f32_e32 v127, v127, v248
	v_sub_f32_e32 v80, v80, v248
	v_sub_f32_e32 v81, v81, v248
	v_sub_f32_e32 v82, v82, v248
	v_sub_f32_e32 v83, v83, v248
	v_sub_f32_e32 v84, v84, v248
	v_sub_f32_e32 v85, v85, v248
	v_sub_f32_e32 v86, v86, v248
	v_sub_f32_e32 v87, v87, v248
	v_sub_f32_e32 v88, v88, v248
	v_sub_f32_e32 v89, v89, v248
	v_sub_f32_e32 v90, v90, v248
	v_sub_f32_e32 v91, v91, v248
	v_sub_f32_e32 v92, v92, v248
	v_sub_f32_e32 v93, v93, v248
	v_sub_f32_e32 v94, v94, v248
	v_sub_f32_e32 v95, v95, v248
	v_add_f32_e32 v188, v188, v248
	v_mul_f32_e32 v189, v189, v250
	v_pk_mul_f32 v[0:1], v[0:1], v[250:251] op_sel_hi:[1,0]
	v_pk_mul_f32 v[2:3], v[2:3], v[250:251] op_sel_hi:[1,0]
	v_pk_mul_f32 v[4:5], v[4:5], v[250:251] op_sel_hi:[1,0]
	v_pk_mul_f32 v[6:7], v[6:7], v[250:251] op_sel_hi:[1,0]
	v_pk_mul_f32 v[8:9], v[8:9], v[250:251] op_sel_hi:[1,0]
	v_pk_mul_f32 v[10:11], v[10:11], v[250:251] op_sel_hi:[1,0]
	v_pk_mul_f32 v[12:13], v[12:13], v[250:251] op_sel_hi:[1,0]
	v_pk_mul_f32 v[14:15], v[14:15], v[250:251] op_sel_hi:[1,0]
	v_pk_mul_f32 v[16:17], v[16:17], v[250:251] op_sel_hi:[1,0]
	v_pk_mul_f32 v[18:19], v[18:19], v[250:251] op_sel_hi:[1,0]
	v_pk_mul_f32 v[20:21], v[20:21], v[250:251] op_sel_hi:[1,0]
	v_pk_mul_f32 v[22:23], v[22:23], v[250:251] op_sel_hi:[1,0]
	v_pk_mul_f32 v[24:25], v[24:25], v[250:251] op_sel_hi:[1,0]
	v_pk_mul_f32 v[26:27], v[26:27], v[250:251] op_sel_hi:[1,0]
	v_pk_mul_f32 v[28:29], v[28:29], v[250:251] op_sel_hi:[1,0]
	v_pk_mul_f32 v[30:31], v[30:31], v[250:251] op_sel_hi:[1,0]
	v_pk_mul_f32 v[32:33], v[32:33], v[250:251] op_sel_hi:[1,0]
	v_pk_mul_f32 v[34:35], v[34:35], v[250:251] op_sel_hi:[1,0]
	v_pk_mul_f32 v[36:37], v[36:37], v[250:251] op_sel_hi:[1,0]
	v_pk_mul_f32 v[38:39], v[38:39], v[250:251] op_sel_hi:[1,0]
	v_pk_mul_f32 v[40:41], v[40:41], v[250:251] op_sel_hi:[1,0]
	v_pk_mul_f32 v[42:43], v[42:43], v[250:251] op_sel_hi:[1,0]
	v_pk_mul_f32 v[44:45], v[44:45], v[250:251] op_sel_hi:[1,0]
	v_pk_mul_f32 v[46:47], v[46:47], v[250:251] op_sel_hi:[1,0]
	v_pk_mul_f32 v[48:49], v[48:49], v[250:251] op_sel_hi:[1,0]
	v_pk_mul_f32 v[50:51], v[50:51], v[250:251] op_sel_hi:[1,0]
	v_pk_mul_f32 v[52:53], v[52:53], v[250:251] op_sel_hi:[1,0]
	v_pk_mul_f32 v[54:55], v[54:55], v[250:251] op_sel_hi:[1,0]
	v_pk_mul_f32 v[56:57], v[56:57], v[250:251] op_sel_hi:[1,0]
	v_pk_mul_f32 v[58:59], v[58:59], v[250:251] op_sel_hi:[1,0]
	v_pk_mul_f32 v[60:61], v[60:61], v[250:251] op_sel_hi:[1,0]
	v_pk_mul_f32 v[62:63], v[62:63], v[250:251] op_sel_hi:[1,0]
	v_sub_f32_e32 v96, 0, v188
	v_mov_b32_e32 v97, v96
	v_mov_b32_e32 v98, v96
	v_mov_b32_e32 v99, v96
	v_mov_b32_e32 v100, v96
	v_mov_b32_e32 v101, v96
	v_mov_b32_e32 v102, v96
	v_mov_b32_e32 v103, v96
	v_mov_b32_e32 v104, v96
	v_mov_b32_e32 v105, v96
	v_mov_b32_e32 v106, v96
	v_mov_b32_e32 v107, v96
	v_mov_b32_e32 v108, v96
	v_mov_b32_e32 v109, v96
	v_mov_b32_e32 v110, v96
	v_mov_b32_e32 v111, v96
	s_branch .Latt_cont_a
